# ffn_in also as 256x128 double tiles sharing one B tile (B double-buffered in LDS, two-pass epilogue)
# speedup vs baseline: 1.0869x; 1.0178x over previous
.LBB0_2352:
	v_and_b32_e32 v2, 15, v0
	v_ashrrev_i32_e32 v3, 1, v0
	s_movk_i32 s8, 0xffc0
	s_waitcnt vmcnt(2)
	v_and_or_b32 v74, v3, s8, v2
	v_lshrrev_b32_e32 v2, 1, v0
	v_lshrrev_b32_e32 v0, 2, v0
	s_and_b32 s17, s2, 7
	v_and_b32_e32 v0, 12, v0
	v_and_or_b32 v75, v2, 32, v0
	v_cvt_f32_ubyte0_e32 v0, s17
	v_rcp_iflag_f32_e32 v0, v0
	s_lshr_b32 s16, s2, 3
	s_cmp_lt_i32 s12, 0
	s_cselect_b64 s[2:3], -1, 0
	v_mul_f32_e32 v0, 0x4f7ffffe, v0
	v_cvt_u32_f32_e32 v0, v0
	s_sub_i32 s8, 0, s17
	s_load_dwordx2 s[4:5], s[0:1], 0x108
	s_load_dwordx2 s[6:7], s[0:1], 0x138
	v_readfirstlane_b32 s9, v0
	s_mul_i32 s8, s8, s9
	s_mul_hi_u32 s8, s9, s8
	s_add_i32 s18, s9, s8
	v_readlane_b32 s8, v249, 52
	v_readlane_b32 s9, v249, 53
	s_mov_b32 s10, s8
	s_mul_i32 s9, s10, 0xb00000
	s_mul_hi_u32 s8, s8, 0xb00000
	s_waitcnt lgkmcnt(0)
	s_add_u32 s19, s4, s9
	s_addc_u32 s20, s5, s8
	s_waitcnt vmcnt(0)
	s_mov_b32 s32, 0
	v_readlane_b32 s30, v249, 1
	s_nop 0
	s_cmpk_lg_u32 s30, 0x200
	s_cbranch_scc1 .LBB0_2354
	s_mov_b32 s48, 0
.Lf2_tile:
	v_readlane_b32 s30, v249, 0
	s_nop 0
	s_and_b32 s31, s30, 7
	s_lshr_b32 s30, s30, 3
	s_cmp_lt_u32 s30, 32
	s_cselect_b32 s35, 6, 5
	s_cmp_lt_u32 s48, s35
	s_cbranch_scc0 .Lf2_extra
	s_lshl_b32 s33, s48, 6
	s_add_i32 s33, s33, s30
	s_cmp_ge_u32 s33, 0xb0
	s_cselect_b32 s34, 1, 0
	s_mul_i32 s8, s34, 0xb0
	s_sub_i32 s33, s33, s8
	s_lshr_b32 s21, s33, 2
	s_and_b32 s33, s33, 3
	s_lshl_b32 s34, s34, 3
	s_add_i32 s33, s33, s34
	s_lshl_b32 s33, s33, 3
	s_add_i32 s8, s33, s31
	s_add_i32 s49, s8, 32
	s_branch .Lf2_go
.Lf2_extra:
	s_cmp_eq_u32 s48, s35
	s_cbranch_scc0 .Lf2_done
	s_cmp_lt_u32 s30, 32
	s_cbranch_scc1 .Lf2_done
	s_sub_i32 s33, s30, 32
	s_lshl_b32 s33, s33, 3
	s_add_i32 s21, s33, s31
	s_cmp_lt_u32 s21, 44
	s_cbranch_scc0 .Lf2_done
	s_movk_i32 s8, 0x80
	s_movk_i32 s49, 0x81
.Lf2_go:
	v_and_b32_e32 v70, 7, v196
	v_bfe_u32 v71, v196, 4, 2
	v_bfe_u32 v72, v196, 6, 1
	v_lshl_or_b32 v73, v72, 2, v71
	v_xor_b32_e32 v70, v70, v73
	v_lshrrev_b32_e32 v73, 3, v196
	v_lshlrev_b32_e32 v73, 11, v73
	v_lshl_or_b32 v76, v70, 4, v73
	v_add_u32_e32 v77, 0x10000, v76
	v_add_u32_e32 v78, 0x20000, v76
	v_add_u32_e32 v79, 0x30000, v76
	v_and_b32_e32 v70, 15, v196
	v_bfe_u32 v73, v196, 1, 3
	v_xor_b32_e32 v73, v71, v73
	v_lshlrev_b32_e32 v73, 4, v73
	v_xor_b32_e32 v82, 64, v73
	v_lshlrev_b32_e32 v70, 7, v70
	v_lshrrev_b32_e32 v83, 7, v196
	v_lshl_or_b32 v83, v83, 13, v70
	v_lshl_or_b32 v84, v72, 13, v70
	v_add_u32_e32 v80, v83, v73
	v_add_u32_e32 v81, v83, v82
	v_add_u32_e32 v144, v84, v73
	v_add_u32_e32 v145, v84, v82
	v_readfirstlane_b32 s64, v196
	s_lshr_b32 s64, s64, 6
	s_lshl_b32 s64, s64, 10
	s_lshl_b32 s30, s8, 18
	s_add_u32 s50, s6, s30
	s_addc_u32 s51, s7, 0
	s_lshl_b32 s30, s49, 18
	s_add_u32 s52, s6, s30
	s_addc_u32 s53, s7, 0
	s_lshl_b32 s30, s21, 18
	s_add_u32 s58, s19, s30
	s_addc_u32 s59, s20, 0
	s_barrier
	s_add_i32 m0, s64, 0x0
	s_nop 0
	global_load_lds_dwordx4 v76, s[50:51]
	s_add_i32 m0, s64, 0x1000
	s_nop 0
	global_load_lds_dwordx4 v77, s[50:51]
	s_add_i32 m0, s64, 0x2000
	s_nop 0
	global_load_lds_dwordx4 v78, s[50:51]
	s_add_i32 m0, s64, 0x3000
	s_nop 0
	global_load_lds_dwordx4 v79, s[50:51]
	s_add_i32 m0, s64, 0x4000
	s_nop 0
	global_load_lds_dwordx4 v76, s[52:53]
	s_add_i32 m0, s64, 0x5000
	s_nop 0
	global_load_lds_dwordx4 v77, s[52:53]
	s_add_i32 m0, s64, 0x6000
	s_nop 0
	global_load_lds_dwordx4 v78, s[52:53]
	s_add_i32 m0, s64, 0x7000
	s_nop 0
	global_load_lds_dwordx4 v79, s[52:53]
	s_add_u32 s50, s50, 0x80
	s_addc_u32 s51, s51, 0
	s_add_u32 s52, s52, 0x80
	s_addc_u32 s53, s53, 0
	s_add_i32 m0, s64, 0x8000
	s_nop 0
	global_load_lds_dwordx4 v76, s[58:59]
	s_add_i32 m0, s64, 0x9000
	s_nop 0
	global_load_lds_dwordx4 v77, s[58:59]
	s_add_i32 m0, s64, 0xa000
	s_nop 0
	global_load_lds_dwordx4 v78, s[58:59]
	s_add_i32 m0, s64, 0xb000
	s_nop 0
	global_load_lds_dwordx4 v79, s[58:59]
	s_add_u32 s58, s58, 0x80
	s_addc_u32 s59, s59, 0
	v_mov_b64_e32 v[62:63], 0
	v_mov_b64_e32 v[64:65], 0
	v_mov_b64_e32 v[54:55], 0
	v_mov_b64_e32 v[56:57], 0
	v_mov_b64_e32 v[58:59], 0
	v_mov_b64_e32 v[60:61], 0
	v_mov_b64_e32 v[50:51], 0
	v_mov_b64_e32 v[52:53], 0
	v_mov_b64_e32 v[46:47], 0
	v_mov_b64_e32 v[48:49], 0
	v_mov_b64_e32 v[38:39], 0
	v_mov_b64_e32 v[40:41], 0
	v_mov_b64_e32 v[42:43], 0
	v_mov_b64_e32 v[44:45], 0
	v_mov_b64_e32 v[34:35], 0
	v_mov_b64_e32 v[36:37], 0
	v_mov_b64_e32 v[30:31], 0
	v_mov_b64_e32 v[32:33], 0
	v_mov_b64_e32 v[22:23], 0
	v_mov_b64_e32 v[24:25], 0
	v_mov_b64_e32 v[26:27], 0
	v_mov_b64_e32 v[28:29], 0
	v_mov_b64_e32 v[18:19], 0
	v_mov_b64_e32 v[20:21], 0
	v_mov_b64_e32 v[14:15], 0
	v_mov_b64_e32 v[16:17], 0
	v_mov_b64_e32 v[6:7], 0
	v_mov_b64_e32 v[8:9], 0
	v_mov_b64_e32 v[10:11], 0
	v_mov_b64_e32 v[12:13], 0
	v_mov_b64_e32 v[2:3], 0
	v_mov_b64_e32 v[4:5], 0
	v_mov_b64_e32 v[66:67], 0
	v_mov_b64_e32 v[68:69], 0
	v_mov_b64_e32 v[70:71], 0
	v_mov_b64_e32 v[72:73], 0
	v_mov_b64_e32 v[82:83], 0
	v_mov_b64_e32 v[84:85], 0
	v_mov_b64_e32 v[86:87], 0
	v_mov_b64_e32 v[88:89], 0
	v_mov_b64_e32 v[90:91], 0
	v_mov_b64_e32 v[92:93], 0
	v_mov_b64_e32 v[94:95], 0
	v_mov_b64_e32 v[96:97], 0
	v_mov_b64_e32 v[98:99], 0
	v_mov_b64_e32 v[100:101], 0
	v_mov_b64_e32 v[102:103], 0
	v_mov_b64_e32 v[104:105], 0
	v_mov_b64_e32 v[106:107], 0
	v_mov_b64_e32 v[108:109], 0
	v_mov_b64_e32 v[110:111], 0
	v_mov_b64_e32 v[112:113], 0
	v_mov_b64_e32 v[114:115], 0
	v_mov_b64_e32 v[116:117], 0
	v_mov_b64_e32 v[118:119], 0
	v_mov_b64_e32 v[120:121], 0
	v_mov_b64_e32 v[122:123], 0
	v_mov_b64_e32 v[124:125], 0
	v_mov_b64_e32 v[126:127], 0
	v_mov_b64_e32 v[128:129], 0
	v_mov_b64_e32 v[136:137], 0
	v_mov_b64_e32 v[138:139], 0
	v_mov_b64_e32 v[140:141], 0
	v_mov_b64_e32 v[142:143], 0
	s_movk_i32 s65, 7
.Lf2_k:
	s_waitcnt vmcnt(0)
	s_barrier
	s_add_i32 m0, s64, 0xc000
	s_nop 0
	global_load_lds_dwordx4 v76, s[58:59]
	s_add_i32 m0, s64, 0xd000
	s_nop 0
	global_load_lds_dwordx4 v77, s[58:59]
	s_add_i32 m0, s64, 0xe000
	s_nop 0
	global_load_lds_dwordx4 v78, s[58:59]
	s_add_i32 m0, s64, 0xf000
	s_nop 0
	global_load_lds_dwordx4 v79, s[58:59]
	s_add_u32 s58, s58, 0x80
	s_addc_u32 s59, s59, 0
	ds_read_b128 v[148:151], v80 offset:0
	ds_read_b128 v[152:155], v80 offset:2048
	ds_read_b128 v[156:159], v80 offset:4096
	ds_read_b128 v[160:163], v80 offset:6144
	ds_read_b128 v[164:167], v80 offset:16384
	ds_read_b128 v[168:171], v80 offset:18432
	ds_read_b128 v[174:177], v80 offset:20480
	ds_read_b128 v[182:185], v80 offset:22528
	ds_read_b128 v[188:191], v144 offset:32768
	ds_read_b128 v[192:195], v144 offset:34816
	ds_read_b128 v[208:211], v144 offset:36864
	ds_read_b128 v[212:215], v144 offset:38912
	s_waitcnt lgkmcnt(0)
	s_setprio 1
	v_mfma_f32_16x16x32_bf16 v[62:65], v[188:191], v[148:151], v[62:65]
	v_mfma_f32_16x16x32_bf16 v[54:57], v[192:195], v[148:151], v[54:57]
	v_mfma_f32_16x16x32_bf16 v[58:61], v[208:211], v[148:151], v[58:61]
	v_mfma_f32_16x16x32_bf16 v[50:53], v[212:215], v[148:151], v[50:53]
	v_mfma_f32_16x16x32_bf16 v[46:49], v[188:191], v[152:155], v[46:49]
	v_mfma_f32_16x16x32_bf16 v[38:41], v[192:195], v[152:155], v[38:41]
	v_mfma_f32_16x16x32_bf16 v[42:45], v[208:211], v[152:155], v[42:45]
	v_mfma_f32_16x16x32_bf16 v[34:37], v[212:215], v[152:155], v[34:37]
	v_mfma_f32_16x16x32_bf16 v[30:33], v[188:191], v[156:159], v[30:33]
	v_mfma_f32_16x16x32_bf16 v[22:25], v[192:195], v[156:159], v[22:25]
	v_mfma_f32_16x16x32_bf16 v[26:29], v[208:211], v[156:159], v[26:29]
	v_mfma_f32_16x16x32_bf16 v[18:21], v[212:215], v[156:159], v[18:21]
	v_mfma_f32_16x16x32_bf16 v[14:17], v[188:191], v[160:163], v[14:17]
	v_mfma_f32_16x16x32_bf16 v[6:9], v[192:195], v[160:163], v[6:9]
	v_mfma_f32_16x16x32_bf16 v[10:13], v[208:211], v[160:163], v[10:13]
	v_mfma_f32_16x16x32_bf16 v[2:5], v[212:215], v[160:163], v[2:5]
	v_mfma_f32_16x16x32_bf16 v[66:69], v[188:191], v[164:167], v[66:69]
	v_mfma_f32_16x16x32_bf16 v[70:73], v[192:195], v[164:167], v[70:73]
	v_mfma_f32_16x16x32_bf16 v[82:85], v[208:211], v[164:167], v[82:85]
	v_mfma_f32_16x16x32_bf16 v[86:89], v[212:215], v[164:167], v[86:89]
	v_mfma_f32_16x16x32_bf16 v[90:93], v[188:191], v[168:171], v[90:93]
	v_mfma_f32_16x16x32_bf16 v[94:97], v[192:195], v[168:171], v[94:97]
	v_mfma_f32_16x16x32_bf16 v[98:101], v[208:211], v[168:171], v[98:101]
	v_mfma_f32_16x16x32_bf16 v[102:105], v[212:215], v[168:171], v[102:105]
	v_mfma_f32_16x16x32_bf16 v[106:109], v[188:191], v[174:177], v[106:109]
	v_mfma_f32_16x16x32_bf16 v[110:113], v[192:195], v[174:177], v[110:113]
	v_mfma_f32_16x16x32_bf16 v[114:117], v[208:211], v[174:177], v[114:117]
	v_mfma_f32_16x16x32_bf16 v[118:121], v[212:215], v[174:177], v[118:121]
	v_mfma_f32_16x16x32_bf16 v[122:125], v[188:191], v[182:185], v[122:125]
	v_mfma_f32_16x16x32_bf16 v[126:129], v[192:195], v[182:185], v[126:129]
	v_mfma_f32_16x16x32_bf16 v[136:139], v[208:211], v[182:185], v[136:139]
	v_mfma_f32_16x16x32_bf16 v[140:143], v[212:215], v[182:185], v[140:143]
	s_setprio 0
	ds_read_b128 v[148:151], v81 offset:0
	ds_read_b128 v[152:155], v81 offset:2048
	ds_read_b128 v[156:159], v81 offset:4096
	ds_read_b128 v[160:163], v81 offset:6144
	ds_read_b128 v[164:167], v81 offset:16384
	ds_read_b128 v[168:171], v81 offset:18432
	ds_read_b128 v[174:177], v81 offset:20480
	ds_read_b128 v[182:185], v81 offset:22528
	ds_read_b128 v[188:191], v145 offset:32768
	ds_read_b128 v[192:195], v145 offset:34816
	ds_read_b128 v[208:211], v145 offset:36864
	ds_read_b128 v[212:215], v145 offset:38912
	s_waitcnt lgkmcnt(0)
	s_barrier
	s_add_i32 m0, s64, 0x0
	s_nop 0
	global_load_lds_dwordx4 v76, s[50:51]
	s_add_i32 m0, s64, 0x1000
	s_nop 0
	global_load_lds_dwordx4 v77, s[50:51]
	s_add_i32 m0, s64, 0x2000
	s_nop 0
	global_load_lds_dwordx4 v78, s[50:51]
	s_add_i32 m0, s64, 0x3000
	s_nop 0
	global_load_lds_dwordx4 v79, s[50:51]
	s_add_i32 m0, s64, 0x4000
	s_nop 0
	global_load_lds_dwordx4 v76, s[52:53]
	s_add_i32 m0, s64, 0x5000
	s_nop 0
	global_load_lds_dwordx4 v77, s[52:53]
	s_add_i32 m0, s64, 0x6000
	s_nop 0
	global_load_lds_dwordx4 v78, s[52:53]
	s_add_i32 m0, s64, 0x7000
	s_nop 0
	global_load_lds_dwordx4 v79, s[52:53]
	s_add_u32 s50, s50, 0x80
	s_addc_u32 s51, s51, 0
	s_add_u32 s52, s52, 0x80
	s_addc_u32 s53, s53, 0
	s_setprio 1
	v_mfma_f32_16x16x32_bf16 v[62:65], v[188:191], v[148:151], v[62:65]
	v_mfma_f32_16x16x32_bf16 v[54:57], v[192:195], v[148:151], v[54:57]
	v_mfma_f32_16x16x32_bf16 v[58:61], v[208:211], v[148:151], v[58:61]
	v_mfma_f32_16x16x32_bf16 v[50:53], v[212:215], v[148:151], v[50:53]
	v_mfma_f32_16x16x32_bf16 v[46:49], v[188:191], v[152:155], v[46:49]
	v_mfma_f32_16x16x32_bf16 v[38:41], v[192:195], v[152:155], v[38:41]
	v_mfma_f32_16x16x32_bf16 v[42:45], v[208:211], v[152:155], v[42:45]
	v_mfma_f32_16x16x32_bf16 v[34:37], v[212:215], v[152:155], v[34:37]
	v_mfma_f32_16x16x32_bf16 v[30:33], v[188:191], v[156:159], v[30:33]
	v_mfma_f32_16x16x32_bf16 v[22:25], v[192:195], v[156:159], v[22:25]
	v_mfma_f32_16x16x32_bf16 v[26:29], v[208:211], v[156:159], v[26:29]
	v_mfma_f32_16x16x32_bf16 v[18:21], v[212:215], v[156:159], v[18:21]
	v_mfma_f32_16x16x32_bf16 v[14:17], v[188:191], v[160:163], v[14:17]
	v_mfma_f32_16x16x32_bf16 v[6:9], v[192:195], v[160:163], v[6:9]
	v_mfma_f32_16x16x32_bf16 v[10:13], v[208:211], v[160:163], v[10:13]
	v_mfma_f32_16x16x32_bf16 v[2:5], v[212:215], v[160:163], v[2:5]
	v_mfma_f32_16x16x32_bf16 v[66:69], v[188:191], v[164:167], v[66:69]
	v_mfma_f32_16x16x32_bf16 v[70:73], v[192:195], v[164:167], v[70:73]
	v_mfma_f32_16x16x32_bf16 v[82:85], v[208:211], v[164:167], v[82:85]
	v_mfma_f32_16x16x32_bf16 v[86:89], v[212:215], v[164:167], v[86:89]
	v_mfma_f32_16x16x32_bf16 v[90:93], v[188:191], v[168:171], v[90:93]
	v_mfma_f32_16x16x32_bf16 v[94:97], v[192:195], v[168:171], v[94:97]
	v_mfma_f32_16x16x32_bf16 v[98:101], v[208:211], v[168:171], v[98:101]
	v_mfma_f32_16x16x32_bf16 v[102:105], v[212:215], v[168:171], v[102:105]
	v_mfma_f32_16x16x32_bf16 v[106:109], v[188:191], v[174:177], v[106:109]
	v_mfma_f32_16x16x32_bf16 v[110:113], v[192:195], v[174:177], v[110:113]
	v_mfma_f32_16x16x32_bf16 v[114:117], v[208:211], v[174:177], v[114:117]
	v_mfma_f32_16x16x32_bf16 v[118:121], v[212:215], v[174:177], v[118:121]
	v_mfma_f32_16x16x32_bf16 v[122:125], v[188:191], v[182:185], v[122:125]
	v_mfma_f32_16x16x32_bf16 v[126:129], v[192:195], v[182:185], v[126:129]
	v_mfma_f32_16x16x32_bf16 v[136:139], v[208:211], v[182:185], v[136:139]
	v_mfma_f32_16x16x32_bf16 v[140:143], v[212:215], v[182:185], v[140:143]
	s_setprio 0
	s_waitcnt vmcnt(0)
	s_barrier
	s_add_i32 m0, s64, 0x8000
	s_nop 0
	global_load_lds_dwordx4 v76, s[58:59]
	s_add_i32 m0, s64, 0x9000
	s_nop 0
	global_load_lds_dwordx4 v77, s[58:59]
	s_add_i32 m0, s64, 0xa000
	s_nop 0
	global_load_lds_dwordx4 v78, s[58:59]
	s_add_i32 m0, s64, 0xb000
	s_nop 0
	global_load_lds_dwordx4 v79, s[58:59]
	s_add_u32 s58, s58, 0x80
	s_addc_u32 s59, s59, 0
	ds_read_b128 v[148:151], v80 offset:0
	ds_read_b128 v[152:155], v80 offset:2048
	ds_read_b128 v[156:159], v80 offset:4096
	ds_read_b128 v[160:163], v80 offset:6144
	ds_read_b128 v[164:167], v80 offset:16384
	ds_read_b128 v[168:171], v80 offset:18432
	ds_read_b128 v[174:177], v80 offset:20480
	ds_read_b128 v[182:185], v80 offset:22528
	ds_read_b128 v[188:191], v144 offset:49152
	ds_read_b128 v[192:195], v144 offset:51200
	ds_read_b128 v[208:211], v144 offset:53248
	ds_read_b128 v[212:215], v144 offset:55296
	s_waitcnt lgkmcnt(0)
	s_setprio 1
	v_mfma_f32_16x16x32_bf16 v[62:65], v[188:191], v[148:151], v[62:65]
	v_mfma_f32_16x16x32_bf16 v[54:57], v[192:195], v[148:151], v[54:57]
	v_mfma_f32_16x16x32_bf16 v[58:61], v[208:211], v[148:151], v[58:61]
	v_mfma_f32_16x16x32_bf16 v[50:53], v[212:215], v[148:151], v[50:53]
	v_mfma_f32_16x16x32_bf16 v[46:49], v[188:191], v[152:155], v[46:49]
	v_mfma_f32_16x16x32_bf16 v[38:41], v[192:195], v[152:155], v[38:41]
	v_mfma_f32_16x16x32_bf16 v[42:45], v[208:211], v[152:155], v[42:45]
	v_mfma_f32_16x16x32_bf16 v[34:37], v[212:215], v[152:155], v[34:37]
	v_mfma_f32_16x16x32_bf16 v[30:33], v[188:191], v[156:159], v[30:33]
	v_mfma_f32_16x16x32_bf16 v[22:25], v[192:195], v[156:159], v[22:25]
	v_mfma_f32_16x16x32_bf16 v[26:29], v[208:211], v[156:159], v[26:29]
	v_mfma_f32_16x16x32_bf16 v[18:21], v[212:215], v[156:159], v[18:21]
	v_mfma_f32_16x16x32_bf16 v[14:17], v[188:191], v[160:163], v[14:17]
	v_mfma_f32_16x16x32_bf16 v[6:9], v[192:195], v[160:163], v[6:9]
	v_mfma_f32_16x16x32_bf16 v[10:13], v[208:211], v[160:163], v[10:13]
	v_mfma_f32_16x16x32_bf16 v[2:5], v[212:215], v[160:163], v[2:5]
	v_mfma_f32_16x16x32_bf16 v[66:69], v[188:191], v[164:167], v[66:69]
	v_mfma_f32_16x16x32_bf16 v[70:73], v[192:195], v[164:167], v[70:73]
	v_mfma_f32_16x16x32_bf16 v[82:85], v[208:211], v[164:167], v[82:85]
	v_mfma_f32_16x16x32_bf16 v[86:89], v[212:215], v[164:167], v[86:89]
	v_mfma_f32_16x16x32_bf16 v[90:93], v[188:191], v[168:171], v[90:93]
	v_mfma_f32_16x16x32_bf16 v[94:97], v[192:195], v[168:171], v[94:97]
	v_mfma_f32_16x16x32_bf16 v[98:101], v[208:211], v[168:171], v[98:101]
	v_mfma_f32_16x16x32_bf16 v[102:105], v[212:215], v[168:171], v[102:105]
	v_mfma_f32_16x16x32_bf16 v[106:109], v[188:191], v[174:177], v[106:109]
	v_mfma_f32_16x16x32_bf16 v[110:113], v[192:195], v[174:177], v[110:113]
	v_mfma_f32_16x16x32_bf16 v[114:117], v[208:211], v[174:177], v[114:117]
	v_mfma_f32_16x16x32_bf16 v[118:121], v[212:215], v[174:177], v[118:121]
	v_mfma_f32_16x16x32_bf16 v[122:125], v[188:191], v[182:185], v[122:125]
	v_mfma_f32_16x16x32_bf16 v[126:129], v[192:195], v[182:185], v[126:129]
	v_mfma_f32_16x16x32_bf16 v[136:139], v[208:211], v[182:185], v[136:139]
	v_mfma_f32_16x16x32_bf16 v[140:143], v[212:215], v[182:185], v[140:143]
	s_setprio 0
	ds_read_b128 v[148:151], v81 offset:0
	ds_read_b128 v[152:155], v81 offset:2048
	ds_read_b128 v[156:159], v81 offset:4096
	ds_read_b128 v[160:163], v81 offset:6144
	ds_read_b128 v[164:167], v81 offset:16384
	ds_read_b128 v[168:171], v81 offset:18432
	ds_read_b128 v[174:177], v81 offset:20480
	ds_read_b128 v[182:185], v81 offset:22528
	ds_read_b128 v[188:191], v145 offset:49152
	ds_read_b128 v[192:195], v145 offset:51200
	ds_read_b128 v[208:211], v145 offset:53248
	ds_read_b128 v[212:215], v145 offset:55296
	s_waitcnt lgkmcnt(0)
	s_barrier
	s_add_i32 m0, s64, 0x0
	s_nop 0
	global_load_lds_dwordx4 v76, s[50:51]
	s_add_i32 m0, s64, 0x1000
	s_nop 0
	global_load_lds_dwordx4 v77, s[50:51]
	s_add_i32 m0, s64, 0x2000
	s_nop 0
	global_load_lds_dwordx4 v78, s[50:51]
	s_add_i32 m0, s64, 0x3000
	s_nop 0
	global_load_lds_dwordx4 v79, s[50:51]
	s_add_i32 m0, s64, 0x4000
	s_nop 0
	global_load_lds_dwordx4 v76, s[52:53]
	s_add_i32 m0, s64, 0x5000
	s_nop 0
	global_load_lds_dwordx4 v77, s[52:53]
	s_add_i32 m0, s64, 0x6000
	s_nop 0
	global_load_lds_dwordx4 v78, s[52:53]
	s_add_i32 m0, s64, 0x7000
	s_nop 0
	global_load_lds_dwordx4 v79, s[52:53]
	s_add_u32 s50, s50, 0x80
	s_addc_u32 s51, s51, 0
	s_add_u32 s52, s52, 0x80
	s_addc_u32 s53, s53, 0
	s_setprio 1
	v_mfma_f32_16x16x32_bf16 v[62:65], v[188:191], v[148:151], v[62:65]
	v_mfma_f32_16x16x32_bf16 v[54:57], v[192:195], v[148:151], v[54:57]
	v_mfma_f32_16x16x32_bf16 v[58:61], v[208:211], v[148:151], v[58:61]
	v_mfma_f32_16x16x32_bf16 v[50:53], v[212:215], v[148:151], v[50:53]
	v_mfma_f32_16x16x32_bf16 v[46:49], v[188:191], v[152:155], v[46:49]
	v_mfma_f32_16x16x32_bf16 v[38:41], v[192:195], v[152:155], v[38:41]
	v_mfma_f32_16x16x32_bf16 v[42:45], v[208:211], v[152:155], v[42:45]
	v_mfma_f32_16x16x32_bf16 v[34:37], v[212:215], v[152:155], v[34:37]
	v_mfma_f32_16x16x32_bf16 v[30:33], v[188:191], v[156:159], v[30:33]
	v_mfma_f32_16x16x32_bf16 v[22:25], v[192:195], v[156:159], v[22:25]
	v_mfma_f32_16x16x32_bf16 v[26:29], v[208:211], v[156:159], v[26:29]
	v_mfma_f32_16x16x32_bf16 v[18:21], v[212:215], v[156:159], v[18:21]
	v_mfma_f32_16x16x32_bf16 v[14:17], v[188:191], v[160:163], v[14:17]
	v_mfma_f32_16x16x32_bf16 v[6:9], v[192:195], v[160:163], v[6:9]
	v_mfma_f32_16x16x32_bf16 v[10:13], v[208:211], v[160:163], v[10:13]
	v_mfma_f32_16x16x32_bf16 v[2:5], v[212:215], v[160:163], v[2:5]
	v_mfma_f32_16x16x32_bf16 v[66:69], v[188:191], v[164:167], v[66:69]
	v_mfma_f32_16x16x32_bf16 v[70:73], v[192:195], v[164:167], v[70:73]
	v_mfma_f32_16x16x32_bf16 v[82:85], v[208:211], v[164:167], v[82:85]
	v_mfma_f32_16x16x32_bf16 v[86:89], v[212:215], v[164:167], v[86:89]
	v_mfma_f32_16x16x32_bf16 v[90:93], v[188:191], v[168:171], v[90:93]
	v_mfma_f32_16x16x32_bf16 v[94:97], v[192:195], v[168:171], v[94:97]
	v_mfma_f32_16x16x32_bf16 v[98:101], v[208:211], v[168:171], v[98:101]
	v_mfma_f32_16x16x32_bf16 v[102:105], v[212:215], v[168:171], v[102:105]
	v_mfma_f32_16x16x32_bf16 v[106:109], v[188:191], v[174:177], v[106:109]
	v_mfma_f32_16x16x32_bf16 v[110:113], v[192:195], v[174:177], v[110:113]
	v_mfma_f32_16x16x32_bf16 v[114:117], v[208:211], v[174:177], v[114:117]
	v_mfma_f32_16x16x32_bf16 v[118:121], v[212:215], v[174:177], v[118:121]
	v_mfma_f32_16x16x32_bf16 v[122:125], v[188:191], v[182:185], v[122:125]
	v_mfma_f32_16x16x32_bf16 v[126:129], v[192:195], v[182:185], v[126:129]
	v_mfma_f32_16x16x32_bf16 v[136:139], v[208:211], v[182:185], v[136:139]
	v_mfma_f32_16x16x32_bf16 v[140:143], v[212:215], v[182:185], v[140:143]
	s_setprio 0
	s_add_i32 s65, s65, -1
	s_cmp_lg_u32 s65, 0
	s_cbranch_scc1 .Lf2_k
	s_waitcnt vmcnt(0)
	s_barrier
	s_add_i32 m0, s64, 0xc000
	s_nop 0
	global_load_lds_dwordx4 v76, s[58:59]
	s_add_i32 m0, s64, 0xd000
	s_nop 0
	global_load_lds_dwordx4 v77, s[58:59]
	s_add_i32 m0, s64, 0xe000
	s_nop 0
	global_load_lds_dwordx4 v78, s[58:59]
	s_add_i32 m0, s64, 0xf000
	s_nop 0
	global_load_lds_dwordx4 v79, s[58:59]
	s_add_u32 s58, s58, 0x80
	s_addc_u32 s59, s59, 0
	ds_read_b128 v[148:151], v80 offset:0
	ds_read_b128 v[152:155], v80 offset:2048
	ds_read_b128 v[156:159], v80 offset:4096
	ds_read_b128 v[160:163], v80 offset:6144
	ds_read_b128 v[164:167], v80 offset:16384
	ds_read_b128 v[168:171], v80 offset:18432
	ds_read_b128 v[174:177], v80 offset:20480
	ds_read_b128 v[182:185], v80 offset:22528
	ds_read_b128 v[188:191], v144 offset:32768
	ds_read_b128 v[192:195], v144 offset:34816
	ds_read_b128 v[208:211], v144 offset:36864
	ds_read_b128 v[212:215], v144 offset:38912
	s_waitcnt lgkmcnt(0)
	s_setprio 1
	v_mfma_f32_16x16x32_bf16 v[62:65], v[188:191], v[148:151], v[62:65]
	v_mfma_f32_16x16x32_bf16 v[54:57], v[192:195], v[148:151], v[54:57]
	v_mfma_f32_16x16x32_bf16 v[58:61], v[208:211], v[148:151], v[58:61]
	v_mfma_f32_16x16x32_bf16 v[50:53], v[212:215], v[148:151], v[50:53]
	v_mfma_f32_16x16x32_bf16 v[46:49], v[188:191], v[152:155], v[46:49]
	v_mfma_f32_16x16x32_bf16 v[38:41], v[192:195], v[152:155], v[38:41]
	v_mfma_f32_16x16x32_bf16 v[42:45], v[208:211], v[152:155], v[42:45]
	v_mfma_f32_16x16x32_bf16 v[34:37], v[212:215], v[152:155], v[34:37]
	v_mfma_f32_16x16x32_bf16 v[30:33], v[188:191], v[156:159], v[30:33]
	v_mfma_f32_16x16x32_bf16 v[22:25], v[192:195], v[156:159], v[22:25]
	v_mfma_f32_16x16x32_bf16 v[26:29], v[208:211], v[156:159], v[26:29]
	v_mfma_f32_16x16x32_bf16 v[18:21], v[212:215], v[156:159], v[18:21]
	v_mfma_f32_16x16x32_bf16 v[14:17], v[188:191], v[160:163], v[14:17]
	v_mfma_f32_16x16x32_bf16 v[6:9], v[192:195], v[160:163], v[6:9]
	v_mfma_f32_16x16x32_bf16 v[10:13], v[208:211], v[160:163], v[10:13]
	v_mfma_f32_16x16x32_bf16 v[2:5], v[212:215], v[160:163], v[2:5]
	v_mfma_f32_16x16x32_bf16 v[66:69], v[188:191], v[164:167], v[66:69]
	v_mfma_f32_16x16x32_bf16 v[70:73], v[192:195], v[164:167], v[70:73]
	v_mfma_f32_16x16x32_bf16 v[82:85], v[208:211], v[164:167], v[82:85]
	v_mfma_f32_16x16x32_bf16 v[86:89], v[212:215], v[164:167], v[86:89]
	v_mfma_f32_16x16x32_bf16 v[90:93], v[188:191], v[168:171], v[90:93]
	v_mfma_f32_16x16x32_bf16 v[94:97], v[192:195], v[168:171], v[94:97]
	v_mfma_f32_16x16x32_bf16 v[98:101], v[208:211], v[168:171], v[98:101]
	v_mfma_f32_16x16x32_bf16 v[102:105], v[212:215], v[168:171], v[102:105]
	v_mfma_f32_16x16x32_bf16 v[106:109], v[188:191], v[174:177], v[106:109]
	v_mfma_f32_16x16x32_bf16 v[110:113], v[192:195], v[174:177], v[110:113]
	v_mfma_f32_16x16x32_bf16 v[114:117], v[208:211], v[174:177], v[114:117]
	v_mfma_f32_16x16x32_bf16 v[118:121], v[212:215], v[174:177], v[118:121]
	v_mfma_f32_16x16x32_bf16 v[122:125], v[188:191], v[182:185], v[122:125]
	v_mfma_f32_16x16x32_bf16 v[126:129], v[192:195], v[182:185], v[126:129]
	v_mfma_f32_16x16x32_bf16 v[136:139], v[208:211], v[182:185], v[136:139]
	v_mfma_f32_16x16x32_bf16 v[140:143], v[212:215], v[182:185], v[140:143]
	s_setprio 0
	ds_read_b128 v[148:151], v81 offset:0
	ds_read_b128 v[152:155], v81 offset:2048
	ds_read_b128 v[156:159], v81 offset:4096
	ds_read_b128 v[160:163], v81 offset:6144
	ds_read_b128 v[164:167], v81 offset:16384
	ds_read_b128 v[168:171], v81 offset:18432
	ds_read_b128 v[174:177], v81 offset:20480
	ds_read_b128 v[182:185], v81 offset:22528
	ds_read_b128 v[188:191], v145 offset:32768
	ds_read_b128 v[192:195], v145 offset:34816
	ds_read_b128 v[208:211], v145 offset:36864
	ds_read_b128 v[212:215], v145 offset:38912
	s_waitcnt lgkmcnt(0)
	s_barrier
	s_add_i32 m0, s64, 0x0
	s_nop 0
	global_load_lds_dwordx4 v76, s[50:51]
	s_add_i32 m0, s64, 0x1000
	s_nop 0
	global_load_lds_dwordx4 v77, s[50:51]
	s_add_i32 m0, s64, 0x2000
	s_nop 0
	global_load_lds_dwordx4 v78, s[50:51]
	s_add_i32 m0, s64, 0x3000
	s_nop 0
	global_load_lds_dwordx4 v79, s[50:51]
	s_add_i32 m0, s64, 0x4000
	s_nop 0
	global_load_lds_dwordx4 v76, s[52:53]
	s_add_i32 m0, s64, 0x5000
	s_nop 0
	global_load_lds_dwordx4 v77, s[52:53]
	s_add_i32 m0, s64, 0x6000
	s_nop 0
	global_load_lds_dwordx4 v78, s[52:53]
	s_add_i32 m0, s64, 0x7000
	s_nop 0
	global_load_lds_dwordx4 v79, s[52:53]
	s_add_u32 s50, s50, 0x80
	s_addc_u32 s51, s51, 0
	s_add_u32 s52, s52, 0x80
	s_addc_u32 s53, s53, 0
	s_setprio 1
	v_mfma_f32_16x16x32_bf16 v[62:65], v[188:191], v[148:151], v[62:65]
	v_mfma_f32_16x16x32_bf16 v[54:57], v[192:195], v[148:151], v[54:57]
	v_mfma_f32_16x16x32_bf16 v[58:61], v[208:211], v[148:151], v[58:61]
	v_mfma_f32_16x16x32_bf16 v[50:53], v[212:215], v[148:151], v[50:53]
	v_mfma_f32_16x16x32_bf16 v[46:49], v[188:191], v[152:155], v[46:49]
	v_mfma_f32_16x16x32_bf16 v[38:41], v[192:195], v[152:155], v[38:41]
	v_mfma_f32_16x16x32_bf16 v[42:45], v[208:211], v[152:155], v[42:45]
	v_mfma_f32_16x16x32_bf16 v[34:37], v[212:215], v[152:155], v[34:37]
	v_mfma_f32_16x16x32_bf16 v[30:33], v[188:191], v[156:159], v[30:33]
	v_mfma_f32_16x16x32_bf16 v[22:25], v[192:195], v[156:159], v[22:25]
	v_mfma_f32_16x16x32_bf16 v[26:29], v[208:211], v[156:159], v[26:29]
	v_mfma_f32_16x16x32_bf16 v[18:21], v[212:215], v[156:159], v[18:21]
	v_mfma_f32_16x16x32_bf16 v[14:17], v[188:191], v[160:163], v[14:17]
	v_mfma_f32_16x16x32_bf16 v[6:9], v[192:195], v[160:163], v[6:9]
	v_mfma_f32_16x16x32_bf16 v[10:13], v[208:211], v[160:163], v[10:13]
	v_mfma_f32_16x16x32_bf16 v[2:5], v[212:215], v[160:163], v[2:5]
	v_mfma_f32_16x16x32_bf16 v[66:69], v[188:191], v[164:167], v[66:69]
	v_mfma_f32_16x16x32_bf16 v[70:73], v[192:195], v[164:167], v[70:73]
	v_mfma_f32_16x16x32_bf16 v[82:85], v[208:211], v[164:167], v[82:85]
	v_mfma_f32_16x16x32_bf16 v[86:89], v[212:215], v[164:167], v[86:89]
	v_mfma_f32_16x16x32_bf16 v[90:93], v[188:191], v[168:171], v[90:93]
	v_mfma_f32_16x16x32_bf16 v[94:97], v[192:195], v[168:171], v[94:97]
	v_mfma_f32_16x16x32_bf16 v[98:101], v[208:211], v[168:171], v[98:101]
	v_mfma_f32_16x16x32_bf16 v[102:105], v[212:215], v[168:171], v[102:105]
	v_mfma_f32_16x16x32_bf16 v[106:109], v[188:191], v[174:177], v[106:109]
	v_mfma_f32_16x16x32_bf16 v[110:113], v[192:195], v[174:177], v[110:113]
	v_mfma_f32_16x16x32_bf16 v[114:117], v[208:211], v[174:177], v[114:117]
	v_mfma_f32_16x16x32_bf16 v[118:121], v[212:215], v[174:177], v[118:121]
	v_mfma_f32_16x16x32_bf16 v[122:125], v[188:191], v[182:185], v[122:125]
	v_mfma_f32_16x16x32_bf16 v[126:129], v[192:195], v[182:185], v[126:129]
	v_mfma_f32_16x16x32_bf16 v[136:139], v[208:211], v[182:185], v[136:139]
	v_mfma_f32_16x16x32_bf16 v[140:143], v[212:215], v[182:185], v[140:143]
	s_setprio 0
	s_waitcnt vmcnt(0)
	s_barrier
	ds_read_b128 v[148:151], v80 offset:0
	ds_read_b128 v[152:155], v80 offset:2048
	ds_read_b128 v[156:159], v80 offset:4096
	ds_read_b128 v[160:163], v80 offset:6144
	ds_read_b128 v[164:167], v80 offset:16384
	ds_read_b128 v[168:171], v80 offset:18432
	ds_read_b128 v[174:177], v80 offset:20480
	ds_read_b128 v[182:185], v80 offset:22528
	ds_read_b128 v[188:191], v144 offset:49152
	ds_read_b128 v[192:195], v144 offset:51200
	ds_read_b128 v[208:211], v144 offset:53248
	ds_read_b128 v[212:215], v144 offset:55296
	s_waitcnt lgkmcnt(0)
	s_setprio 1
	v_mfma_f32_16x16x32_bf16 v[62:65], v[188:191], v[148:151], v[62:65]
	v_mfma_f32_16x16x32_bf16 v[54:57], v[192:195], v[148:151], v[54:57]
	v_mfma_f32_16x16x32_bf16 v[58:61], v[208:211], v[148:151], v[58:61]
	v_mfma_f32_16x16x32_bf16 v[50:53], v[212:215], v[148:151], v[50:53]
	v_mfma_f32_16x16x32_bf16 v[46:49], v[188:191], v[152:155], v[46:49]
	v_mfma_f32_16x16x32_bf16 v[38:41], v[192:195], v[152:155], v[38:41]
	v_mfma_f32_16x16x32_bf16 v[42:45], v[208:211], v[152:155], v[42:45]
	v_mfma_f32_16x16x32_bf16 v[34:37], v[212:215], v[152:155], v[34:37]
	v_mfma_f32_16x16x32_bf16 v[30:33], v[188:191], v[156:159], v[30:33]
	v_mfma_f32_16x16x32_bf16 v[22:25], v[192:195], v[156:159], v[22:25]
	v_mfma_f32_16x16x32_bf16 v[26:29], v[208:211], v[156:159], v[26:29]
	v_mfma_f32_16x16x32_bf16 v[18:21], v[212:215], v[156:159], v[18:21]
	v_mfma_f32_16x16x32_bf16 v[14:17], v[188:191], v[160:163], v[14:17]
	v_mfma_f32_16x16x32_bf16 v[6:9], v[192:195], v[160:163], v[6:9]
	v_mfma_f32_16x16x32_bf16 v[10:13], v[208:211], v[160:163], v[10:13]
	v_mfma_f32_16x16x32_bf16 v[2:5], v[212:215], v[160:163], v[2:5]
	v_mfma_f32_16x16x32_bf16 v[66:69], v[188:191], v[164:167], v[66:69]
	v_mfma_f32_16x16x32_bf16 v[70:73], v[192:195], v[164:167], v[70:73]
	v_mfma_f32_16x16x32_bf16 v[82:85], v[208:211], v[164:167], v[82:85]
	v_mfma_f32_16x16x32_bf16 v[86:89], v[212:215], v[164:167], v[86:89]
	v_mfma_f32_16x16x32_bf16 v[90:93], v[188:191], v[168:171], v[90:93]
	v_mfma_f32_16x16x32_bf16 v[94:97], v[192:195], v[168:171], v[94:97]
	v_mfma_f32_16x16x32_bf16 v[98:101], v[208:211], v[168:171], v[98:101]
	v_mfma_f32_16x16x32_bf16 v[102:105], v[212:215], v[168:171], v[102:105]
	v_mfma_f32_16x16x32_bf16 v[106:109], v[188:191], v[174:177], v[106:109]
	v_mfma_f32_16x16x32_bf16 v[110:113], v[192:195], v[174:177], v[110:113]
	v_mfma_f32_16x16x32_bf16 v[114:117], v[208:211], v[174:177], v[114:117]
	v_mfma_f32_16x16x32_bf16 v[118:121], v[212:215], v[174:177], v[118:121]
	v_mfma_f32_16x16x32_bf16 v[122:125], v[188:191], v[182:185], v[122:125]
	v_mfma_f32_16x16x32_bf16 v[126:129], v[192:195], v[182:185], v[126:129]
	v_mfma_f32_16x16x32_bf16 v[136:139], v[208:211], v[182:185], v[136:139]
	v_mfma_f32_16x16x32_bf16 v[140:143], v[212:215], v[182:185], v[140:143]
	s_setprio 0
	ds_read_b128 v[148:151], v81 offset:0
	ds_read_b128 v[152:155], v81 offset:2048
	ds_read_b128 v[156:159], v81 offset:4096
	ds_read_b128 v[160:163], v81 offset:6144
	ds_read_b128 v[164:167], v81 offset:16384
	ds_read_b128 v[168:171], v81 offset:18432
	ds_read_b128 v[174:177], v81 offset:20480
	ds_read_b128 v[182:185], v81 offset:22528
	ds_read_b128 v[188:191], v145 offset:49152
	ds_read_b128 v[192:195], v145 offset:51200
	ds_read_b128 v[208:211], v145 offset:53248
	ds_read_b128 v[212:215], v145 offset:55296
	s_waitcnt lgkmcnt(0)
	s_setprio 1
	v_mfma_f32_16x16x32_bf16 v[62:65], v[188:191], v[148:151], v[62:65]
	v_mfma_f32_16x16x32_bf16 v[54:57], v[192:195], v[148:151], v[54:57]
	v_mfma_f32_16x16x32_bf16 v[58:61], v[208:211], v[148:151], v[58:61]
	v_mfma_f32_16x16x32_bf16 v[50:53], v[212:215], v[148:151], v[50:53]
	v_mfma_f32_16x16x32_bf16 v[46:49], v[188:191], v[152:155], v[46:49]
	v_mfma_f32_16x16x32_bf16 v[38:41], v[192:195], v[152:155], v[38:41]
	v_mfma_f32_16x16x32_bf16 v[42:45], v[208:211], v[152:155], v[42:45]
	v_mfma_f32_16x16x32_bf16 v[34:37], v[212:215], v[152:155], v[34:37]
	v_mfma_f32_16x16x32_bf16 v[30:33], v[188:191], v[156:159], v[30:33]
	v_mfma_f32_16x16x32_bf16 v[22:25], v[192:195], v[156:159], v[22:25]
	v_mfma_f32_16x16x32_bf16 v[26:29], v[208:211], v[156:159], v[26:29]
	v_mfma_f32_16x16x32_bf16 v[18:21], v[212:215], v[156:159], v[18:21]
	v_mfma_f32_16x16x32_bf16 v[14:17], v[188:191], v[160:163], v[14:17]
	v_mfma_f32_16x16x32_bf16 v[6:9], v[192:195], v[160:163], v[6:9]
	v_mfma_f32_16x16x32_bf16 v[10:13], v[208:211], v[160:163], v[10:13]
	v_mfma_f32_16x16x32_bf16 v[2:5], v[212:215], v[160:163], v[2:5]
	v_mfma_f32_16x16x32_bf16 v[66:69], v[188:191], v[164:167], v[66:69]
	v_mfma_f32_16x16x32_bf16 v[70:73], v[192:195], v[164:167], v[70:73]
	v_mfma_f32_16x16x32_bf16 v[82:85], v[208:211], v[164:167], v[82:85]
	v_mfma_f32_16x16x32_bf16 v[86:89], v[212:215], v[164:167], v[86:89]
	v_mfma_f32_16x16x32_bf16 v[90:93], v[188:191], v[168:171], v[90:93]
	v_mfma_f32_16x16x32_bf16 v[94:97], v[192:195], v[168:171], v[94:97]
	v_mfma_f32_16x16x32_bf16 v[98:101], v[208:211], v[168:171], v[98:101]
	v_mfma_f32_16x16x32_bf16 v[102:105], v[212:215], v[168:171], v[102:105]
	v_mfma_f32_16x16x32_bf16 v[106:109], v[188:191], v[174:177], v[106:109]
	v_mfma_f32_16x16x32_bf16 v[110:113], v[192:195], v[174:177], v[110:113]
	v_mfma_f32_16x16x32_bf16 v[114:117], v[208:211], v[174:177], v[114:117]
	v_mfma_f32_16x16x32_bf16 v[118:121], v[212:215], v[174:177], v[118:121]
	v_mfma_f32_16x16x32_bf16 v[122:125], v[188:191], v[182:185], v[122:125]
	v_mfma_f32_16x16x32_bf16 v[126:129], v[192:195], v[182:185], v[126:129]
	v_mfma_f32_16x16x32_bf16 v[136:139], v[208:211], v[182:185], v[136:139]
	v_mfma_f32_16x16x32_bf16 v[140:143], v[212:215], v[182:185], v[140:143]
	s_setprio 0
	s_nop 7
	s_nop 7
	s_nop 7
	v_mov_b32_e32 v148, v66
	v_mov_b32_e32 v149, v67
	v_mov_b32_e32 v150, v68
	v_mov_b32_e32 v151, v69
	v_mov_b32_e32 v152, v70
	v_mov_b32_e32 v153, v71
	v_mov_b32_e32 v154, v72
	v_mov_b32_e32 v155, v73
	v_mov_b32_e32 v156, v82
	v_mov_b32_e32 v157, v83
	v_mov_b32_e32 v158, v84
	v_mov_b32_e32 v159, v85
	v_mov_b32_e32 v160, v86
	v_mov_b32_e32 v161, v87
	v_mov_b32_e32 v162, v88
	v_mov_b32_e32 v163, v89
	v_mov_b32_e32 v164, v90
	v_mov_b32_e32 v165, v91
	v_mov_b32_e32 v166, v92
	v_mov_b32_e32 v167, v93
	v_mov_b32_e32 v168, v94
	v_mov_b32_e32 v169, v95
	v_mov_b32_e32 v170, v96
	v_mov_b32_e32 v171, v97
	v_mov_b32_e32 v174, v98
	v_mov_b32_e32 v175, v99
	v_mov_b32_e32 v176, v100
	v_mov_b32_e32 v177, v101
	v_mov_b32_e32 v182, v102
	v_mov_b32_e32 v183, v103
	v_mov_b32_e32 v184, v104
	v_mov_b32_e32 v185, v105
	v_mov_b32_e32 v188, v106
	v_mov_b32_e32 v189, v107
	v_mov_b32_e32 v190, v108
	v_mov_b32_e32 v191, v109
	v_mov_b32_e32 v192, v110
	v_mov_b32_e32 v193, v111
	v_mov_b32_e32 v194, v112
	v_mov_b32_e32 v195, v113
	v_mov_b32_e32 v208, v114
	v_mov_b32_e32 v209, v115
	v_mov_b32_e32 v210, v116
	v_mov_b32_e32 v211, v117
	v_mov_b32_e32 v212, v118
	v_mov_b32_e32 v213, v119
	v_mov_b32_e32 v214, v120
	v_mov_b32_e32 v215, v121
	v_mov_b32_e32 v216, v122
	v_mov_b32_e32 v217, v123
	v_mov_b32_e32 v218, v124
	v_mov_b32_e32 v219, v125
	v_mov_b32_e32 v220, v126
	v_mov_b32_e32 v221, v127
	v_mov_b32_e32 v222, v128
	v_mov_b32_e32 v223, v129
	v_mov_b32_e32 v242, v136
	v_mov_b32_e32 v243, v137
	v_mov_b32_e32 v244, v138
	v_mov_b32_e32 v245, v139
	v_mov_b32_e32 v199, v140
	v_mov_b32_e32 v206, v141
	v_mov_b32_e32 v207, v142
	v_mov_b32_e32 v226, v143
	s_mov_b32 s32, 1
	s_branch .LBB0_2353
.Lf2_ret:
	s_cmp_eq_u32 s32, 1
	s_cbranch_scc0 .Lf2_next
	s_mov_b32 s32, 2
	s_mov_b32 s8, s49
	v_mov_b32_e32 v62, v148
	v_mov_b32_e32 v63, v149
	v_mov_b32_e32 v64, v150
	v_mov_b32_e32 v65, v151
	v_mov_b32_e32 v54, v152
	v_mov_b32_e32 v55, v153
	v_mov_b32_e32 v56, v154
	v_mov_b32_e32 v57, v155
	v_mov_b32_e32 v58, v156
	v_mov_b32_e32 v59, v157
	v_mov_b32_e32 v60, v158
	v_mov_b32_e32 v61, v159
	v_mov_b32_e32 v50, v160
	v_mov_b32_e32 v51, v161
	v_mov_b32_e32 v52, v162
	v_mov_b32_e32 v53, v163
	v_mov_b32_e32 v46, v164
	v_mov_b32_e32 v47, v165
	v_mov_b32_e32 v48, v166
	v_mov_b32_e32 v49, v167
	v_mov_b32_e32 v38, v168
	v_mov_b32_e32 v39, v169
	v_mov_b32_e32 v40, v170
	v_mov_b32_e32 v41, v171
	v_mov_b32_e32 v42, v174
	v_mov_b32_e32 v43, v175
	v_mov_b32_e32 v44, v176
	v_mov_b32_e32 v45, v177
	v_mov_b32_e32 v34, v182
	v_mov_b32_e32 v35, v183
	v_mov_b32_e32 v36, v184
	v_mov_b32_e32 v37, v185
	v_mov_b32_e32 v30, v188
	v_mov_b32_e32 v31, v189
	v_mov_b32_e32 v32, v190
	v_mov_b32_e32 v33, v191
	v_mov_b32_e32 v22, v192
	v_mov_b32_e32 v23, v193
	v_mov_b32_e32 v24, v194
	v_mov_b32_e32 v25, v195
	v_mov_b32_e32 v26, v208
	v_mov_b32_e32 v27, v209
	v_mov_b32_e32 v28, v210
	v_mov_b32_e32 v29, v211
	v_mov_b32_e32 v18, v212
	v_mov_b32_e32 v19, v213
	v_mov_b32_e32 v20, v214
	v_mov_b32_e32 v21, v215
	v_mov_b32_e32 v14, v216
	v_mov_b32_e32 v15, v217
	v_mov_b32_e32 v16, v218
	v_mov_b32_e32 v17, v219
	v_mov_b32_e32 v6, v220
	v_mov_b32_e32 v7, v221
	v_mov_b32_e32 v8, v222
	v_mov_b32_e32 v9, v223
	v_mov_b32_e32 v10, v242
	v_mov_b32_e32 v11, v243
	v_mov_b32_e32 v12, v244
	v_mov_b32_e32 v13, v245
	v_mov_b32_e32 v2, v199
	v_mov_b32_e32 v3, v206
	v_mov_b32_e32 v4, v207
	v_mov_b32_e32 v5, v226
	s_branch .LBB0_2353

.LBB0_2353:
	v_mul_f32_e32 v70, 0xbfb8aa3b, v62
	v_mul_f32_e32 v71, 0xbfb8aa3b, v63
	v_exp_f32_e32 v70, v70
	v_exp_f32_e32 v71, v71
	v_lshl_add_u32 v0, s8, 7, v74
	s_load_dwordx2 s[8:9], s[0:1], 0x1c0
	v_add_f32_e32 v70, 1.0, v70
	v_add_f32_e32 v71, 1.0, v71
	v_rcp_f32_e32 v70, v70
	v_rcp_f32_e32 v71, v71
	v_lshl_or_b32 v66, s21, 6, v75
	v_ashrrev_i32_e32 v67, 31, v66
	s_waitcnt lgkmcnt(0)
	v_lshl_add_u64 v[66:67], v[66:67], 1, s[8:9]
	v_pk_mul_f32 v[62:63], v[62:63], v[70:71]
	s_movk_i32 s10, 0x1600
	v_pk_mul_f32 v[58:59], v[58:59], v[62:63]
	v_mul_f32_e32 v62, 0xbfb8aa3b, v64
	v_mul_f32_e32 v63, 0xbfb8aa3b, v65
	v_exp_f32_e32 v62, v62
	v_exp_f32_e32 v63, v63
	v_mad_i64_i32 v[68:69], s[8:9], v0, s10, v[66:67]
	v_add_f32_e32 v62, 1.0, v62
	v_add_f32_e32 v63, 1.0, v63
	v_rcp_f32_e32 v62, v62
	v_rcp_f32_e32 v63, v63
	v_cvt_pk_bf16_f32 v58, v58, v59
	s_add_i32 s13, s13, s14
	s_cmp_lt_i32 s13, s15
	v_pk_mul_f32 v[62:63], v[64:65], v[62:63]
	s_movk_i32 s26, 0x3fff
	v_pk_mul_f32 v[60:61], v[60:61], v[62:63]
	s_nop 0
	v_cvt_pk_bf16_f32 v59, v60, v61
	global_store_dwordx2 v[68:69], v[58:59], off
	v_mul_f32_e32 v58, 0xbfb8aa3b, v54
	v_mul_f32_e32 v59, 0xbfb8aa3b, v55
	v_exp_f32_e32 v58, v58
	v_exp_f32_e32 v59, v59
	v_add_f32_e32 v58, 1.0, v58
	v_add_f32_e32 v59, 1.0, v59
	v_rcp_f32_e32 v58, v58
	v_rcp_f32_e32 v59, v59
	s_nop 0
	v_pk_mul_f32 v[54:55], v[54:55], v[58:59]
	s_nop 0
	v_pk_mul_f32 v[50:51], v[50:51], v[54:55]
	v_mul_f32_e32 v54, 0xbfb8aa3b, v56
	v_mul_f32_e32 v55, 0xbfb8aa3b, v57
	v_exp_f32_e32 v54, v54
	v_exp_f32_e32 v55, v55
	v_cvt_pk_bf16_f32 v50, v50, v51
	v_add_f32_e32 v54, 1.0, v54
	v_add_f32_e32 v55, 1.0, v55
	v_rcp_f32_e32 v54, v54
	v_rcp_f32_e32 v55, v55
	s_nop 0
	v_pk_mul_f32 v[54:55], v[56:57], v[54:55]
	s_nop 0
	v_pk_mul_f32 v[52:53], v[52:53], v[54:55]
	s_nop 0
	v_cvt_pk_bf16_f32 v51, v52, v53
	v_mul_f32_e32 v52, 0xbfb8aa3b, v46
	v_mul_f32_e32 v53, 0xbfb8aa3b, v47
	v_exp_f32_e32 v52, v52
	v_exp_f32_e32 v53, v53
	global_store_dwordx2 v[68:69], v[50:51], off offset:32
	v_or_b32_e32 v50, 16, v0
	v_add_f32_e32 v52, 1.0, v52
	v_add_f32_e32 v53, 1.0, v53
	v_rcp_f32_e32 v52, v52
	v_rcp_f32_e32 v53, v53
	v_mad_i64_i32 v[50:51], s[8:9], v50, s10, v[66:67]
	v_pk_mul_f32 v[46:47], v[46:47], v[52:53]
	s_nop 0
	v_pk_mul_f32 v[42:43], v[42:43], v[46:47]
	v_mul_f32_e32 v46, 0xbfb8aa3b, v48
	v_mul_f32_e32 v47, 0xbfb8aa3b, v49
	v_exp_f32_e32 v46, v46
	v_exp_f32_e32 v47, v47
	v_cvt_pk_bf16_f32 v42, v42, v43
	v_add_f32_e32 v46, 1.0, v46
	v_add_f32_e32 v47, 1.0, v47
	v_rcp_f32_e32 v46, v46
	v_rcp_f32_e32 v47, v47
	s_nop 0
	v_pk_mul_f32 v[46:47], v[48:49], v[46:47]
	s_nop 0
	v_pk_mul_f32 v[44:45], v[44:45], v[46:47]
	s_nop 0
	v_cvt_pk_bf16_f32 v43, v44, v45
	global_store_dwordx2 v[50:51], v[42:43], off
	v_mul_f32_e32 v42, 0xbfb8aa3b, v38
	v_mul_f32_e32 v43, 0xbfb8aa3b, v39
	v_exp_f32_e32 v42, v42
	v_exp_f32_e32 v43, v43
	v_add_f32_e32 v42, 1.0, v42
	v_add_f32_e32 v43, 1.0, v43
	v_rcp_f32_e32 v42, v42
	v_rcp_f32_e32 v43, v43
	s_nop 0
	v_pk_mul_f32 v[38:39], v[38:39], v[42:43]
	s_nop 0
	v_pk_mul_f32 v[34:35], v[34:35], v[38:39]
	v_mul_f32_e32 v38, 0xbfb8aa3b, v40
	v_mul_f32_e32 v39, 0xbfb8aa3b, v41
	v_exp_f32_e32 v38, v38
	v_exp_f32_e32 v39, v39
	v_cvt_pk_bf16_f32 v34, v34, v35
	v_add_f32_e32 v38, 1.0, v38
	v_add_f32_e32 v39, 1.0, v39
	v_rcp_f32_e32 v38, v38
	v_rcp_f32_e32 v39, v39
	s_nop 0
	v_pk_mul_f32 v[38:39], v[40:41], v[38:39]
	s_nop 0
	v_pk_mul_f32 v[36:37], v[36:37], v[38:39]
	s_nop 0
	v_cvt_pk_bf16_f32 v35, v36, v37
	v_mul_f32_e32 v36, 0xbfb8aa3b, v30
	v_mul_f32_e32 v37, 0xbfb8aa3b, v31
	v_exp_f32_e32 v36, v36
	v_exp_f32_e32 v37, v37
	global_store_dwordx2 v[50:51], v[34:35], off offset:32
	v_or_b32_e32 v34, 32, v0
	v_add_f32_e32 v36, 1.0, v36
	v_add_f32_e32 v37, 1.0, v37
	v_rcp_f32_e32 v36, v36
	v_rcp_f32_e32 v37, v37
	v_mad_i64_i32 v[34:35], s[8:9], v34, s10, v[66:67]
	v_or_b32_e32 v0, 48, v0
	v_pk_mul_f32 v[30:31], v[30:31], v[36:37]
	s_nop 0
	v_pk_mul_f32 v[26:27], v[26:27], v[30:31]
	v_mul_f32_e32 v30, 0xbfb8aa3b, v32
	v_mul_f32_e32 v31, 0xbfb8aa3b, v33
	v_exp_f32_e32 v30, v30
	v_exp_f32_e32 v31, v31
	v_cvt_pk_bf16_f32 v26, v26, v27
	v_add_f32_e32 v30, 1.0, v30
	v_add_f32_e32 v31, 1.0, v31
	v_rcp_f32_e32 v30, v30
	v_rcp_f32_e32 v31, v31
	s_nop 0
	v_pk_mul_f32 v[30:31], v[32:33], v[30:31]
	s_nop 0
	v_pk_mul_f32 v[28:29], v[28:29], v[30:31]
	s_nop 0
	v_cvt_pk_bf16_f32 v27, v28, v29
	global_store_dwordx2 v[34:35], v[26:27], off
	v_mul_f32_e32 v26, 0xbfb8aa3b, v22
	v_mul_f32_e32 v27, 0xbfb8aa3b, v23
	v_exp_f32_e32 v26, v26
	v_exp_f32_e32 v27, v27
	v_add_f32_e32 v26, 1.0, v26
	v_add_f32_e32 v27, 1.0, v27
	v_rcp_f32_e32 v26, v26
	v_rcp_f32_e32 v27, v27
	s_nop 0
	v_pk_mul_f32 v[22:23], v[22:23], v[26:27]
	s_nop 0
	v_pk_mul_f32 v[18:19], v[18:19], v[22:23]
	v_mul_f32_e32 v22, 0xbfb8aa3b, v24
	v_mul_f32_e32 v23, 0xbfb8aa3b, v25
	v_exp_f32_e32 v22, v22
	v_exp_f32_e32 v23, v23
	v_cvt_pk_bf16_f32 v18, v18, v19
	v_add_f32_e32 v22, 1.0, v22
	v_add_f32_e32 v23, 1.0, v23
	v_rcp_f32_e32 v22, v22
	v_rcp_f32_e32 v23, v23
	s_nop 0
	v_pk_mul_f32 v[22:23], v[24:25], v[22:23]
	s_nop 0
	v_pk_mul_f32 v[20:21], v[20:21], v[22:23]
	s_nop 0
	v_cvt_pk_bf16_f32 v19, v20, v21
	global_store_dwordx2 v[34:35], v[18:19], off offset:32
	v_mad_i64_i32 v[18:19], s[8:9], v0, s10, v[66:67]
	v_mul_f32_e32 v0, 0xbfb8aa3b, v14
	v_exp_f32_e32 v0, v0
	s_nop 0
	v_add_f32_e32 v0, 1.0, v0
	v_rcp_f32_e32 v20, v0
	v_mul_f32_e32 v0, 0xbfb8aa3b, v15
	v_exp_f32_e32 v0, v0
	s_nop 0
	v_add_f32_e32 v0, 1.0, v0
	v_rcp_f32_e32 v21, v0
	v_mul_f32_e32 v0, 0xbfb8aa3b, v16
	v_exp_f32_e32 v0, v0
	v_pk_mul_f32 v[14:15], v[14:15], v[20:21]
	s_nop 0
	v_pk_mul_f32 v[10:11], v[10:11], v[14:15]
	v_add_f32_e32 v0, 1.0, v0
	v_rcp_f32_e32 v14, v0
	v_mul_f32_e32 v0, 0xbfb8aa3b, v17
	v_exp_f32_e32 v0, v0
	v_cvt_pk_bf16_f32 v10, v10, v11
	v_add_f32_e32 v0, 1.0, v0
	v_rcp_f32_e32 v15, v0
	v_mul_f32_e32 v0, 0xbfb8aa3b, v6
	v_exp_f32_e32 v0, v0
	v_pk_mul_f32 v[14:15], v[16:17], v[14:15]
	s_nop 0
	v_pk_mul_f32 v[12:13], v[12:13], v[14:15]
	v_add_f32_e32 v0, 1.0, v0
	v_cvt_pk_bf16_f32 v11, v12, v13
	global_store_dwordx2 v[18:19], v[10:11], off
	v_rcp_f32_e32 v10, v0
	v_mul_f32_e32 v0, 0xbfb8aa3b, v7
	v_exp_f32_e32 v0, v0
	s_nop 0
	v_add_f32_e32 v0, 1.0, v0
	v_rcp_f32_e32 v11, v0
	v_mul_f32_e32 v0, 0xbfb8aa3b, v8
	v_exp_f32_e32 v0, v0
	v_pk_mul_f32 v[6:7], v[6:7], v[10:11]
	s_nop 0
	v_pk_mul_f32 v[2:3], v[2:3], v[6:7]
	v_add_f32_e32 v0, 1.0, v0
	v_rcp_f32_e32 v6, v0
	v_mul_f32_e32 v0, 0xbfb8aa3b, v9
	v_exp_f32_e32 v0, v0
	v_cvt_pk_bf16_f32 v2, v2, v3
	v_add_f32_e32 v0, 1.0, v0
	v_rcp_f32_e32 v7, v0
	s_nop 0
	v_pk_mul_f32 v[6:7], v[8:9], v[6:7]
	s_nop 0
	v_pk_mul_f32 v[4:5], v[4:5], v[6:7]
	s_nop 0
	v_cvt_pk_bf16_f32 v3, v4, v5
	global_store_dwordx2 v[18:19], v[2:3], off offset:32
	s_cmp_lg_u32 s32, 0
	s_cbranch_scc1 .Lf2_ret
	s_cmp_lt_i32 s13, s15
	s_cbranch_scc0 .LBB0_2362
